# attention set-up input loads issued by waves 1-7 before the P1->P2 barrier (wave 0 keeps them after it and now hits L2)
# speedup vs baseline: 1.0033x; 1.0033x over previous
.LBB0_325:
	s_waitcnt vmcnt(0)
	v_readlane_b32 s0, v254, 22
	v_readlane_b32 s1, v254, 23
	s_and_b64 vcc, exec, s[0:1]
	s_waitcnt vmcnt(0)
	v_readlane_b32 s99, v254, 25
	s_nop 3
	s_cmp_eq_u32 s99, 0
	s_cbranch_scc1 .Lcpf_skip
	v_mbcnt_lo_u32_b32 v199, -1, 0
	v_mbcnt_hi_u32_b32 v199, -1, v199
	v_lshlrev_b32_e32 v199, 2, v199
	v_readlane_b32 s100, v254, 18
	v_readlane_b32 s101, v254, 19
	s_nop 4
	global_load_dword v200, v199, s[100:101]
	global_load_dword v201, v199, s[100:101] offset:256
	global_load_dword v202, v199, s[100:101] offset:512
	global_load_dword v203, v199, s[100:101] offset:768
	v_readlane_b32 s100, v254, 14
	v_readlane_b32 s101, v254, 15
	s_nop 4
	global_load_dword v204, v199, s[100:101]
	v_readlane_b32 s100, v254, 16
	v_readlane_b32 s101, v254, 17
	s_nop 4
	global_load_dword v205, v199, s[100:101]
.Lcpf_skip:
	s_barrier
	s_cbranch_vccnz .LBB0_379
	v_mbcnt_lo_u32_b32 v0, -1, 0
	v_mbcnt_hi_u32_b32 v0, -1, v0
	s_nop 0
	v_cmp_eq_u32_e32 vcc, 0, v0
	s_and_saveexec_b64 s[0:1], vcc
	s_cbranch_execz .LBB0_378
	s_add_i32 s2, 0, 0x21000
	v_mov_b32_e32 v0, s2
	s_waitcnt vmcnt(0) expcnt(0) lgkmcnt(0)
	ds_read_b32 v2, v0
	s_add_i32 s2, 0, 0x21004
	v_mov_b32_e32 v0, s2
	ds_read_b32 v0, v0
	s_waitcnt lgkmcnt(1)
	v_cmp_ne_u32_e32 vcc, 0, v2
	s_cbranch_vccnz .LBB0_342
	s_add_u32 s4, s74, 0xfa00200
	s_addc_u32 s5, s75, 0
	s_add_u32 s6, s74, 0xfa00400
	s_addc_u32 s7, s75, 0
	s_add_u32 s8, s74, 0xfa00500
	s_addc_u32 s9, s75, 0
	s_add_u32 s10, s74, 0xfa00600
	s_addc_u32 s11, s75, 0
	s_add_u32 s12, s74, 0xfa00700
	s_addc_u32 s13, s75, 0
	s_add_u32 s14, s74, 0xfa00800
	s_addc_u32 s15, s75, 0
	s_add_u32 s16, s74, 0xfa00900
	s_addc_u32 s17, s75, 0
	s_add_u32 s18, s74, 0xfa00a00
	s_addc_u32 s19, s75, 0
	s_add_u32 s20, s74, 0xfa00b00
	s_addc_u32 s21, s75, 0
	s_add_u32 s22, s74, 0xfa00c00
	s_addc_u32 s23, s75, 0
	s_add_u32 s24, s74, 0xfa00d00
	s_addc_u32 s25, s75, 0
	s_add_u32 s26, s74, 0xfa00e00
	s_addc_u32 s27, s75, 0
	s_add_u32 s28, s74, 0xfa00f00
	s_addc_u32 s29, s75, 0
	s_add_u32 s30, s74, 0xfa01000
	s_addc_u32 s31, s75, 0
	s_add_u32 s34, s74, 0xfa01100
	s_addc_u32 s35, s75, 0
	s_add_u32 s36, s74, 0xfa01200
	v_readlane_b32 s2, v254, 4
	s_addc_u32 s37, s75, 0
	s_mul_i32 s2, s79, s2
	s_add_u32 s38, s74, 0xfa01300
	s_mul_i32 s2, s2, s78
	s_addc_u32 s39, s75, 0
	s_mov_b32 s3, 1
	v_mov_b32_e32 v16, 0
	s_branch .LBB0_330

.LBB0_379:
	s_cmpk_lt_i32 s67, 0x200
	s_cselect_b64 s[0:1], -1, 0
	v_writelane_b32 v254, s0, 62
	s_and_b64 vcc, exec, s[0:1]
	s_waitcnt lgkmcnt(0)
	v_writelane_b32 v254, s1, 63
	s_barrier
	v_mbcnt_lo_u32_b32 v0, -1, 0
	v_mbcnt_hi_u32_b32 v0, -1, v0
	v_lshlrev_b32_e32 v199, 2, v0
	v_readlane_b32 s99, v254, 25
	s_nop 3
	s_cmp_lg_u32 s99, 0
	s_cbranch_scc1 .Lcpf_have
	v_readlane_b32 s100, v254, 18
	v_readlane_b32 s101, v254, 19
	s_nop 4
	global_load_dword v200, v199, s[100:101]
	global_load_dword v201, v199, s[100:101] offset:256
	global_load_dword v202, v199, s[100:101] offset:512
	global_load_dword v203, v199, s[100:101] offset:768
	v_readlane_b32 s100, v254, 14
	v_readlane_b32 s101, v254, 15
	s_nop 4
	global_load_dword v204, v199, s[100:101]
	v_readlane_b32 s100, v254, 16
	v_readlane_b32 s101, v254, 17
	s_nop 4
	global_load_dword v205, v199, s[100:101]
.Lcpf_have:
	s_cmp_lg_u32 s98, 0
	s_cbranch_scc0 .Lst_norm
	s_cmp_lt_u32 s67, 0x80
	s_cbranch_scc0 .Lst_norm
	s_waitcnt vmcnt(0)
	v_readlane_b32 s0, v254, 25
	s_nop 3
	s_lshl_b32 s12, s0, 4
	s_branch .Lrk_noarr
